# stacked: dilated K/V staging loads batched, rowpass next-row prefetch, rowpass global instead of flat memory ops
# speedup vs baseline: 1.0060x; 1.0060x over previous
; __global__ void __launch_bounds__(NTHR) mega(Params p) {
;     ...
;       for (int it = blockIdx.x; it < 3 * 4 * 8 * 32; it += gridDim.x) {
;         const int g = it / 1024, rem = it & 1023;
;         const int b = rem >> 8, hd = (rem >> 5) & 7, q8 = rem & 31;
;         const int sh = (g == 0) ? 0 : (g == 1 ? 2 : 4);
;         const int dil = 1 << sh;
;         const int tpc = 256 >> sh;
;         const int qt0 = q8 * 8;
;         const int cr = qt0 / tpc, ti0 = qt0 - cr * tpc, ti = ti0 + wv;
;         const size_t tb = (size_t)b * SEQ + cr;
;         u16* KsL = (u16*)smem;
;         u16* VsL = KsL + 384 * 72;
;         const u16* kgl = Kk + tb * 1536 + g * 512 + hd * 64;
;         const u16* vgl = Vt + ((size_t)((b * 3 + g) * 8 + hd) * 64) * SEQ + (size_t)cr * (SEQ >> sh);
;         const int kp00 = 32 * ti0 - 128;
;         __syncthreads();
; #pragma unroll
;         for (int i = 0; i < 6; ++i) {
;           const int c = tid + NTHR * i;
;           const int prow = c >> 3, ch = c & 7;
;           int kp = kp00 + prow; if (kp < 0) kp = 0;
;           *(uint4*)(KsL + prow * 72 + ch * 8) = *(const uint4*)(kgl + (size_t)kp * dil * 1536 + ch * 8);
;         }
; #pragma unroll
;         for (int i = 0; i < 6; ++i) {
;           const int c = tid + NTHR * i;
;           const int dv = c / 48, ch = c - dv * 48;
;           int kp = kp00 + 8 * ch; if (kp < 0) kp = 0;
;           *(uint4*)(VsL + dv * 392 + ch * 8) = *(const uint4*)(vgl + (size_t)dv * SEQ + kp);
;         }
;         __syncthreads();
.LBB0_3127:
	s_ashr_i32 s6, s12, 31
	s_lshr_b32 s6, s6, 22
	s_add_i32 s6, s12, s6
	s_and_b32 s18, s11, 0xf8
	s_ashr_i32 s8, s6, 10
	s_bfe_u32 s21, s12, 0x20008
	s_bfe_u32 s14, s12, 0x30005
	s_add_i32 s6, s12, 0x3ff
	s_and_b32 s7, s12, 0xfffffc00
	s_cmpk_eq_i32 s7, 0x400
	s_cselect_b32 s7, 2, 4
	s_cmpk_gt_u32 s6, 0x7fe
	s_cselect_b32 s13, s7, 0
	s_lshl_b32 s6, s12, 3
	s_and_b32 s6, s6, 0xf8
	s_sub_i32 s7, 8, s13
	s_lshr_b32 s24, s6, s7
	s_lshl_b32 s19, s24, s7
	s_sub_i32 s17, s6, s19
	s_lshl_b32 s6, s21, 13
	s_or_b32 s15, s24, s6
	s_mul_i32 s9, s15, 0xc00
	s_add_u32 s16, s30, s9
	s_addc_u32 s20, s31, 0
	s_lshl_b32 s6, s8, 9
	s_ashr_i32 s7, s6, 31
	s_lshl_b64 s[6:7], s[6:7], 1
	s_add_u32 s22, s16, s6
	s_addc_u32 s23, s20, s7
	s_lshl_b32 s16, s14, 6
	s_lshl_b32 s20, s14, 7
	s_add_u32 s22, s22, s20
	s_addc_u32 s23, s23, 0
	s_lshl_b32 s25, s17, 5
	s_addk_i32 s25, 0xff80
	v_add_u32_e32 v2, s25, v99
	v_max_i32_e32 v2, 0, v2
	v_mov_b32_e32 v3, v1
	v_lshl_add_u64 v[6:7], s[22:23], 0, v[0:1]
	v_lshlrev_b64 v[2:3], s13, v[2:3]
	v_mad_u64_u32 v[4:5], s[22:23], v2, s69, v[6:7]
	v_mad_u32_u24 v5, v3, s69, v5
	s_barrier
	global_load_dwordx4 v[176:179], v[4:5], off
	v_add_u32_e32 v8, s25, v71
	v_mov_b32_e32 v9, v1
	v_max_i32_e32 v8, 0, v8
	v_lshlrev_b64 v[8:9], s13, v[8:9]
	v_mad_u64_u32 v[10:11], s[22:23], v8, s69, v[6:7]
	v_mad_u32_u24 v11, v9, s69, v11
	v_add_u32_e32 v8, s25, v73
	v_mov_b32_e32 v9, v1
	v_max_i32_e32 v8, 0, v8
	v_lshlrev_b64 v[8:9], s13, v[8:9]
	s_mul_i32 s21, s21, 3
	s_add_i32 s21, s21, s8
	s_lshl_b32 s21, s21, 3
	v_mov_b32_e32 v44, 0
	v_mov_b32_e32 v43, 0xf149f2ca
	v_mov_b32_e32 v115, v114
	v_mov_b32_e32 v116, v112
	v_mov_b32_e32 v117, v111
	v_mov_b32_e32 v18, 0
	v_mov_b32_e32 v19, v44
	v_mov_b32_e32 v20, v44
	v_mov_b32_e32 v21, v44
	v_mov_b32_e32 v22, v44
	v_mov_b32_e32 v23, v44
	v_mov_b32_e32 v24, v44
	v_mov_b32_e32 v25, v44
	v_mov_b32_e32 v26, v44
	v_mov_b32_e32 v27, v44
	v_mov_b32_e32 v28, v44
	v_mov_b32_e32 v29, v44
	v_mov_b32_e32 v30, v44
	v_mov_b32_e32 v31, v44
	v_mov_b32_e32 v32, v44
	v_mov_b32_e32 v33, v44
	v_mov_b32_e32 v12, v44
	v_mov_b32_e32 v13, v44
	v_mov_b32_e32 v14, v44
	v_mov_b32_e32 v15, v44
	v_mov_b32_e32 v16, v44
	v_mov_b32_e32 v17, v44
	global_load_dwordx4 v[180:183], v[10:11], off
	v_mad_u64_u32 v[10:11], s[22:23], v8, s69, v[6:7]
	v_mad_u32_u24 v11, v9, s69, v11
	v_add_u32_e32 v8, s25, v75
	v_mov_b32_e32 v9, v1
	v_max_i32_e32 v8, 0, v8
	v_lshlrev_b64 v[8:9], s13, v[8:9]
	global_load_dwordx4 v[184:187], v[10:11], off
	v_mad_u64_u32 v[10:11], s[22:23], v8, s69, v[6:7]
	v_mad_u32_u24 v11, v9, s69, v11
	v_add_u32_e32 v8, s25, v77
	v_mov_b32_e32 v9, v1
	v_max_i32_e32 v8, 0, v8
	v_lshlrev_b64 v[8:9], s13, v[8:9]
	global_load_dwordx4 v[188:191], v[10:11], off
	v_mad_u64_u32 v[10:11], s[22:23], v8, s69, v[6:7]
	v_mad_u32_u24 v11, v9, s69, v11
	v_add_u32_e32 v8, s25, v79
	v_mov_b32_e32 v9, v1
	v_max_i32_e32 v8, 0, v8
	v_lshlrev_b64 v[8:9], s13, v[8:9]
	v_mad_u64_u32 v[6:7], s[22:23], v8, s69, v[6:7]
	v_mad_u32_u24 v7, v9, s69, v7
	s_sub_i32 s22, 13, s13
	s_lshl_b32 s24, s24, s22
	s_or_b32 s22, s21, s14
	s_ashr_i32 s23, s22, 31
	s_lshl_b64 s[22:23], s[22:23], 20
	s_add_u32 s21, s34, s22
	s_addc_u32 s23, s35, s23
	s_lshl_b32 s22, s24, 1
	s_add_u32 s22, s21, s22
	s_addc_u32 s23, s23, 0
	v_lshl_add_u64 v[8:9], s[22:23], 0, v[82:83]
	s_add_i32 s17, s17, s10
	s_add_u32 s9, s84, s9
	s_addc_u32 s21, s85, 0
	s_add_u32 s6, s9, s6
	s_addc_u32 s7, s21, s7
	s_add_u32 s6, s6, s20
	s_addc_u32 s7, s7, 0
	s_lshl_b32 s17, s17, 5
	s_lshl_b32 s9, 0xc00, s13
	v_or_b32_e32 v94, s17, v97
	v_ashrrev_i32_e32 v95, 31, v94
	global_load_dwordx4 v[192:195], v[10:11], off
	v_mov_b32_e32 v10, v44
	v_mov_b32_e32 v11, v44
	global_load_dwordx4 v[196:199], v[6:7], off
	v_add_u32_e32 v6, s25, v81
	v_max_i32_e32 v6, 0, v6
	v_mov_b32_e32 v7, v1
	v_lshlrev_b32_e32 v6, 1, v6
	v_lshl_add_u64 v[6:7], v[8:9], 0, v[6:7]
	v_lshl_add_u64 v[8:9], s[22:23], 0, v[84:85]
	global_load_dwordx4 v[200:203], v[6:7], off
	v_add_u32_e32 v6, s25, v101
	v_max_i32_e32 v6, 0, v6
	v_mov_b32_e32 v7, v1
	v_lshlrev_b32_e32 v6, 1, v6
	v_lshl_add_u64 v[6:7], v[8:9], 0, v[6:7]
	v_lshl_add_u64 v[8:9], s[22:23], 0, v[86:87]
	global_load_dwordx4 v[204:207], v[6:7], off
	v_add_u32_e32 v6, s25, v103
	v_max_i32_e32 v6, 0, v6
	v_mov_b32_e32 v7, v1
	v_lshlrev_b32_e32 v6, 1, v6
	v_lshl_add_u64 v[6:7], v[8:9], 0, v[6:7]
	v_lshl_add_u64 v[8:9], s[22:23], 0, v[88:89]
	global_load_dwordx4 v[208:211], v[6:7], off
	v_add_u32_e32 v6, s25, v105
	v_max_i32_e32 v6, 0, v6
	v_mov_b32_e32 v7, v1
	v_lshlrev_b32_e32 v6, 1, v6
	v_lshl_add_u64 v[6:7], v[8:9], 0, v[6:7]
	v_lshl_add_u64 v[8:9], s[22:23], 0, v[90:91]
	global_load_dwordx4 v[212:215], v[6:7], off
	v_add_u32_e32 v6, s25, v107
	v_max_i32_e32 v6, 0, v6
	v_mov_b32_e32 v7, v1
	v_lshlrev_b32_e32 v6, 1, v6
	v_lshl_add_u64 v[6:7], v[8:9], 0, v[6:7]
	v_lshl_add_u64 v[8:9], s[22:23], 0, v[92:93]
	global_load_dwordx4 v[216:219], v[6:7], off
	v_add_u32_e32 v6, s25, v109
	v_max_i32_e32 v6, 0, v6
	v_mov_b32_e32 v7, v1
	v_lshlrev_b32_e32 v6, 1, v6
	v_lshl_add_u64 v[6:7], v[8:9], 0, v[6:7]
	v_mov_b32_e32 v8, v44
	v_mov_b32_e32 v9, v44
	global_load_dwordx4 v[220:223], v[6:7], off
	v_mov_b64_e32 v[6:7], s[6:7]
	v_mad_i64_i32 v[6:7], s[6:7], s9, v94, v[6:7]
	v_lshl_add_u64 v[6:7], v[66:67], 1, v[6:7]
	s_add_i32 s6, s10, s18
	s_sub_i32 s6, s6, s19
	s_mov_b32 s9, 0
	s_lshl_b32 s18, s6, 5
	s_waitcnt vmcnt(0)
	ds_write_b128 v70, v[176:179]
	ds_write_b128 v72, v[180:183]
	ds_write_b128 v74, v[184:187]
	ds_write_b128 v76, v[188:191]
	ds_write_b128 v78, v[192:195]
	ds_write_b128 v80, v[196:199]
	ds_write_b128 v100, v[200:203]
	ds_write_b128 v102, v[204:207]
	ds_write_b128 v104, v[208:211]
	ds_write_b128 v106, v[212:215]
	ds_write_b128 v108, v[216:219]
	ds_write_b128 v110, v[220:223]
	s_waitcnt lgkmcnt(0)
	s_barrier
	flat_load_dwordx4 v[50:53], v[6:7]
	flat_load_dwordx4 v[54:57], v[6:7] offset:32
	flat_load_dwordx4 v[58:61], v[6:7] offset:64
	flat_load_dwordx4 v[62:65], v[6:7] offset:96
	v_mov_b32_e32 v2, 0
	v_mov_b32_e32 v3, v44
	v_mov_b32_e32 v4, v44
	v_mov_b32_e32 v5, v44
	v_mov_b32_e32 v6, v44
	v_mov_b32_e32 v7, v44

; DI float bflo(unsigned u) { return __uint_as_float(u << 16); }
; DI float bfhi(unsigned u) { return __uint_as_float(u & 0xffff0000u); }
; DI void rowpass(const int wave_s, const float* __restrict__ xin, u16* __restrict__ X, const u16* __restrict__ Y, const float* __restrict__ gpost,
;                 const float* __restrict__ gpre, u16* __restrict__ HN, float* __restrict__ outf) {
;     ...
;   for (int row = blockIdx.x * 8 + wv; row < TOK; row += gridDim.x * 8) {
;     float4 x[4];
;     if (Y) {
;       float4 y[4];
;       float ss = 0.f;
; #pragma unroll
;       for (int j = 0; j < 4; ++j) {
;         const uint2 yu = *(const uint2*)(Y + (size_t)row * 1024 + j * 256 + lane * 4);
;         y[j] = make_float4(bflo(yu.x), bfhi(yu.x), bflo(yu.y), bfhi(yu.y));
;         ss += y[j].x * y[j].x + y[j].y * y[j].y + y[j].z * y[j].z + y[j].w * y[j].w;
;       }
;       ss = wsum(ss);
;       const float rs = rsqrtf(ss * (1.f / 1024.f) + 1e-6f);
; #pragma unroll
;       for (int j = 0; j < 4; ++j) {
;         const float4 g = *(const float4*)(gpost + j * 256 + lane * 4);
;         const uint2 xu = *(const uint2*)(X + (size_t)row * 1024 + j * 256 + lane * 4);
.LBB0_3258:
	v_readlane_b32 s4, v254, 10
	v_readlane_b32 s5, v254, 11
	s_waitcnt lgkmcnt(0)
	s_barrier
	s_add_u32 s10, s86, 0x2000000
	s_addc_u32 s11, s87, 0
	s_nop 0
	global_load_dwordx2 v[2:3], v1, s[4:5] offset:24
	s_mov_b32 s4, s6
	v_readlane_b32 s5, v254, 26
	s_add_i32 s6, s4, s5
	s_mul_i32 s12, s93, 0x1800
	s_mov_b32 s13, s67
	v_mov_b32_e32 v0, v171
	s_cmpk_gt_i32 s6, 0x7fff
	s_waitcnt vmcnt(0)
	v_readfirstlane_b32 s4, v3
	v_readfirstlane_b32 s5, v2
	s_cbranch_scc1 .LBB0_3264
	s_lshl_b64 s[8:9], s[12:13], 2
	s_add_u32 s8, s5, s8
	v_lshlrev_b32_e32 v18, 2, v0
	s_addc_u32 s9, s4, s9
	v_ashrrev_i32_e32 v19, 31, v18
	v_lshl_add_u64 v[22:23], v[18:19], 2, s[8:9]
	s_mov_b64 s[4:5], 0x1000
	v_lshl_add_u64 v[14:15], v[22:23], 0, s[4:5]
	s_movk_i32 s4, 0x1000
	v_add_co_u32_e32 v10, vcc, s4, v22
	v_lshlrev_b64 v[24:25], 1, v[18:19]
	s_nop 0
	v_addc_co_u32_e32 v11, vcc, 0, v23, vcc
	flat_load_dwordx4 v[2:5], v[14:15] offset:1024
	flat_load_dwordx4 v[6:9], v[14:15] offset:2048
	s_nop 0
	flat_load_dwordx4 v[10:13], v[10:11]
	s_nop 0
	flat_load_dwordx4 v[14:17], v[14:15] offset:3072
	s_cmp_lg_u64 s[0:1], 0
	s_mov_b64 s[4:5], 0x2000
	v_lshl_add_u64 v[18:19], s[88:89], 0, v[24:25]
	v_lshl_add_u64 v[20:21], s[10:11], 0, v[24:25]
	s_cselect_b64 s[8:9], -1, 0
	v_lshl_add_u64 v[22:23], v[22:23], 0, s[4:5]
	v_lshl_add_u64 v[24:25], s[0:1], 0, v[24:25]
	s_mov_b32 s16, 0x800000
	flat_load_dwordx4 v[100:103], v[22:23]
	flat_load_dwordx4 v[104:107], v[22:23] offset:1024
	flat_load_dwordx4 v[108:111], v[22:23] offset:2048
	flat_load_dwordx4 v[112:115], v[22:23] offset:3072
	s_ashr_i32 s7, s6, 31
	s_lshl_b64 s[14:15], s[6:7], 11
	v_lshl_add_u64 v[132:133], v[18:19], 0, s[14:15]
	global_load_dwordx2 v[116:117], v[132:133], off
	global_load_dwordx2 v[118:119], v[132:133], off offset:512
	global_load_dwordx2 v[120:121], v[132:133], off offset:1024
	global_load_dwordx2 v[122:123], v[132:133], off offset:1536
	v_lshl_add_u64 v[132:133], v[20:21], 0, s[14:15]
	global_load_dwordx2 v[124:125], v[132:133], off
	global_load_dwordx2 v[126:127], v[132:133], off offset:512
	global_load_dwordx2 v[128:129], v[132:133], off offset:1024
	global_load_dwordx2 v[130:131], v[132:133], off offset:1536
	s_branch .LBB0_3261

; DI float bflo(unsigned u) { return __uint_as_float(u << 16); }
; DI float bfhi(unsigned u) { return __uint_as_float(u & 0xffff0000u); }
; DI void rowpass(const int wave_s, const float* __restrict__ xin, u16* __restrict__ X, const u16* __restrict__ Y, const float* __restrict__ gpost,
;                 const float* __restrict__ gpre, u16* __restrict__ HN, float* __restrict__ outf) {
;     ...
;     if (Y) {
;       float4 y[4];
;       float ss = 0.f;
; #pragma unroll
;       for (int j = 0; j < 4; ++j) {
;         const uint2 yu = *(const uint2*)(Y + (size_t)row * 1024 + j * 256 + lane * 4);
;         y[j] = make_float4(bflo(yu.x), bfhi(yu.x), bflo(yu.y), bfhi(yu.y));
;         ss += y[j].x * y[j].x + y[j].y * y[j].y + y[j].z * y[j].z + y[j].w * y[j].w;
;       }
;       ss = wsum(ss);
;       const float rs = rsqrtf(ss * (1.f / 1024.f) + 1e-6f);
; #pragma unroll
;       for (int j = 0; j < 4; ++j) {
;         const float4 g = *(const float4*)(gpost + j * 256 + lane * 4);
;         const uint2 xu = *(const uint2*)(X + (size_t)row * 1024 + j * 256 + lane * 4);
;         x[j] = make_float4(bflo(xu.x), bfhi(xu.x), bflo(xu.y), bfhi(xu.y));
;         x[j].x += y[j].x * rs * g.x; x[j].y += y[j].y * rs * g.y; x[j].z += y[j].z * rs * g.z; x[j].w += y[j].w * rs * g.w;
;       }
;     } else {
; #pragma unroll
;       for (int j = 0; j < 4; ++j) x[j] = *(const float4*)(xin + (size_t)row * 1024 + j * 256 + lane * 4);
;     }
;     float ss2 = 0.f;
; #pragma unroll
;     for (int j = 0; j < 4; ++j) {
;       if (outf) *(float4*)(outf + (size_t)row * 1024 + j * 256 + lane * 4) = x[j];
;       else { uint2 xp; xp.x = pack2(x[j].x, x[j].y); xp.y = pack2(x[j].z, x[j].w); *(uint2*)(X + (size_t)row * 1024 + j * 256 + lane * 4) = xp; }
;       ss2 += x[j].x * x[j].x + x[j].y * x[j].y + x[j].z * x[j].z + x[j].w * x[j].w;
;     }
.LBB0_3261:
	s_ashr_i32 s7, s6, 31
	s_lshl_b64 s[14:15], s[6:7], 11
	v_lshl_add_u64 v[44:45], v[20:21], 0, s[14:15]
	s_waitcnt vmcnt(0) lgkmcnt(0)
	v_mov_b64_e32 v[28:29], v[116:117]
	v_mov_b64_e32 v[30:31], v[118:119]
	v_mov_b64_e32 v[32:33], v[120:121]
	v_mov_b64_e32 v[26:27], v[122:123]
	v_mov_b64_e32 v[34:35], v[124:125]
	v_mov_b64_e32 v[36:37], v[126:127]
	v_mov_b64_e32 v[38:39], v[128:129]
	v_mov_b64_e32 v[40:41], v[130:131]
	s_add_i32 s4, s6, s54
	s_cmp_lt_i32 s4, 0x8000
	s_cbranch_scc0 .Lrp0_nopf
	s_ashr_i32 s5, s4, 31
	s_lshl_b64 s[4:5], s[4:5], 11
	v_lshl_add_u64 v[132:133], v[18:19], 0, s[4:5]
	global_load_dwordx2 v[116:117], v[132:133], off
	global_load_dwordx2 v[118:119], v[132:133], off offset:512
	global_load_dwordx2 v[120:121], v[132:133], off offset:1024
	global_load_dwordx2 v[122:123], v[132:133], off offset:1536
	v_lshl_add_u64 v[132:133], v[20:21], 0, s[4:5]
	global_load_dwordx2 v[124:125], v[132:133], off
	global_load_dwordx2 v[126:127], v[132:133], off offset:512
	global_load_dwordx2 v[128:129], v[132:133], off offset:1024
	global_load_dwordx2 v[130:131], v[132:133], off offset:1536
.Lrp0_nopf:
	s_andn2_b64 vcc, exec, s[8:9]
	v_and_b32_e32 v43, 0xffff0000, v28
	v_and_b32_e32 v47, 0xffff0000, v30
	v_lshlrev_b32_e32 v42, 16, v28
	v_lshlrev_b32_e32 v46, 16, v30
	v_and_b32_e32 v49, 0xffff0000, v32
	v_and_b32_e32 v51, 0xffff0000, v26
	v_mov_b32_e32 v58, v43
	v_mov_b32_e32 v59, v47
	v_lshlrev_b32_e32 v28, 16, v29
	v_lshlrev_b32_e32 v30, 16, v31
	v_lshlrev_b32_e32 v48, 16, v32
	v_lshlrev_b32_e32 v50, 16, v26
	v_mov_b32_e32 v56, v42
	v_mov_b32_e32 v57, v46
	v_mov_b32_e32 v66, v49
	v_mov_b32_e32 v67, v51
	v_pk_mul_f32 v[58:59], v[58:59], v[58:59]
	v_and_b32_e32 v29, 0xffff0000, v29
	v_and_b32_e32 v31, 0xffff0000, v31
	v_lshlrev_b32_e32 v32, 16, v33
	v_lshlrev_b32_e32 v26, 16, v27
	v_mov_b32_e32 v52, v28
	v_mov_b32_e32 v53, v30
	v_mov_b32_e32 v64, v48
	v_mov_b32_e32 v65, v50
	v_pk_mul_f32 v[66:67], v[66:67], v[66:67]
	v_pk_fma_f32 v[56:57], v[56:57], v[56:57], v[58:59]
	v_and_b32_e32 v33, 0xffff0000, v33
	v_and_b32_e32 v27, 0xffff0000, v27
	v_mov_b32_e32 v54, v29
	v_mov_b32_e32 v55, v31
	v_mov_b32_e32 v60, v32
	v_mov_b32_e32 v61, v26
	v_pk_fma_f32 v[58:59], v[64:65], v[64:65], v[66:67]
	v_pk_fma_f32 v[52:53], v[52:53], v[52:53], v[56:57]
	v_mov_b32_e32 v62, v33
	v_mov_b32_e32 v63, v27
	v_pk_fma_f32 v[56:57], v[60:61], v[60:61], v[58:59]
	v_pk_fma_f32 v[52:53], v[54:55], v[54:55], v[52:53]
	v_pk_fma_f32 v[54:55], v[62:63], v[62:63], v[56:57]
	v_add_f32_e32 v0, v52, v53
	v_add_f32_e32 v0, v0, v54
	v_add_f32_e32 v0, v0, v55
	v_mov_b32_e32 v52, v0
	s_nop 1
	v_permlane32_swap_b32_e32 v0, v52
	v_lshlrev_b32_e32 v56, 16, v38
	v_lshlrev_b32_e32 v58, 16, v39
	v_and_b32_e32 v59, 0xffff0000, v39
	v_lshlrev_b32_e32 v54, 16, v36
	s_waitcnt lgkmcnt(0)
	v_add_f32_e32 v0, v0, v52
	v_mov_b32_e32 v52, v0
	s_nop 1
	v_permlane16_swap_b32_e32 v0, v52
	v_lshlrev_b32_e32 v60, 16, v40
	v_lshlrev_b32_e32 v62, 16, v41
	v_and_b32_e32 v63, 0xffff0000, v41
	s_waitcnt lgkmcnt(0)
	v_add_f32_e32 v0, v0, v52
	s_nop 1
	v_mov_b32_dpp v53, v0 row_ror:8 row_mask:0xf bank_mask:0xf
	v_lshlrev_b32_e32 v52, 16, v34
	s_waitcnt lgkmcnt(0)
	v_add_f32_e32 v0, v0, v53
	s_nop 1
	v_mov_b32_dpp v55, v0 row_ror:4 row_mask:0xf bank_mask:0xf
	v_and_b32_e32 v53, 0xffff0000, v34
	v_lshlrev_b32_e32 v34, 16, v35
	v_and_b32_e32 v35, 0xffff0000, v35
	s_waitcnt lgkmcnt(0)
	v_add_f32_e32 v0, v0, v55
	s_nop 1
	v_mov_b32_dpp v57, v0 row_ror:2 row_mask:0xf bank_mask:0xf
	v_and_b32_e32 v55, 0xffff0000, v36
	v_lshlrev_b32_e32 v36, 16, v37
	v_and_b32_e32 v37, 0xffff0000, v37
	s_waitcnt lgkmcnt(0)
	v_add_f32_e32 v0, v0, v57
	s_nop 1
	v_mov_b32_dpp v61, v0 row_ror:1 row_mask:0xf bank_mask:0xf
	v_and_b32_e32 v57, 0xffff0000, v38
	s_waitcnt lgkmcnt(0)
	v_add_f32_e32 v0, v0, v61
	v_fmamk_f32 v0, v0, 0x3a800000, v170
	v_mul_f32_e32 v38, 0x4b800000, v0
	v_cmp_gt_f32_e64 s[4:5], s16, v0
	v_and_b32_e32 v61, 0xffff0000, v40
	s_nop 0
	v_cndmask_b32_e64 v0, v0, v38, s[4:5]
	v_rsq_f32_e32 v0, v0
	s_nop 0
	v_mul_f32_e32 v38, 0x45800000, v0
	v_cndmask_b32_e64 v0, v0, v38, s[4:5]
	v_pk_mul_f32 v[38:39], v[0:1], v[42:43] op_sel_hi:[0,1]
	v_pk_mul_f32 v[28:29], v[0:1], v[28:29] op_sel_hi:[0,1]
	v_pk_mul_f32 v[46:47], v[0:1], v[46:47] op_sel_hi:[0,1]
	v_pk_mul_f32 v[30:31], v[0:1], v[30:31] op_sel_hi:[0,1]
	v_pk_mul_f32 v[48:49], v[0:1], v[48:49] op_sel_hi:[0,1]
	v_pk_mul_f32 v[32:33], v[0:1], v[32:33] op_sel_hi:[0,1]
	v_pk_mul_f32 v[50:51], v[0:1], v[50:51] op_sel_hi:[0,1]
	v_pk_mul_f32 v[26:27], v[0:1], v[26:27] op_sel_hi:[0,1]
	v_pk_fma_f32 v[42:43], v[10:11], v[38:39], v[52:53]
	v_pk_fma_f32 v[40:41], v[12:13], v[28:29], v[34:35]
	v_pk_fma_f32 v[38:39], v[2:3], v[46:47], v[54:55]
	v_pk_fma_f32 v[36:37], v[4:5], v[30:31], v[36:37]
	v_pk_fma_f32 v[34:35], v[6:7], v[48:49], v[56:57]
	v_pk_fma_f32 v[32:33], v[32:33], v[8:9], v[58:59]
	v_pk_fma_f32 v[30:31], v[50:51], v[14:15], v[60:61]
	v_pk_fma_f32 v[28:29], v[26:27], v[16:17], v[62:63]
	v_cvt_pk_bf16_f32 v26, v42, v43
	v_cvt_pk_bf16_f32 v27, v40, v41
	v_cvt_pk_bf16_f32 v46, v38, v39
	v_cvt_pk_bf16_f32 v47, v36, v37
	v_cvt_pk_bf16_f32 v48, v34, v35
	v_cvt_pk_bf16_f32 v49, v32, v33
	v_cvt_pk_bf16_f32 v50, v30, v31
	v_cvt_pk_bf16_f32 v51, v28, v29
	global_store_dwordx2 v[44:45], v[26:27], off
	global_store_dwordx2 v[44:45], v[46:47], off offset:512
	global_store_dwordx2 v[44:45], v[48:49], off offset:1024
	global_store_dwordx2 v[44:45], v[50:51], off offset:1536
	s_cbranch_vccnz .LBB0_3260
; DI void rowpass(const int wave_s, const float* __restrict__ xin, u16* __restrict__ X, const u16* __restrict__ Y, const float* __restrict__ gpost,
;                 const float* __restrict__ gpre, u16* __restrict__ HN, float* __restrict__ outf) {
;     ...
;     if (HN) {
;       ss2 = wsum(ss2);
;       const float rs2 = rsqrtf(ss2 * (1.f / 1024.f) + 1e-6f);
; #pragma unroll
;       for (int j = 0; j < 4; ++j) {
;         const float4 g = *(const float4*)(gpre + j * 256 + lane * 4);
;         uint2 pk;
;         pk.x = pack2(x[j].x * rs2 * g.x, x[j].y * rs2 * g.y);
;         pk.y = pack2(x[j].z * rs2 * g.z, x[j].w * rs2 * g.w);
;         *(uint2*)(HN + (size_t)row * 1024 + j * 256 + lane * 4) = pk;
;       }
	v_mov_b32_e32 v44, v43
	v_mov_b32_e32 v45, v39
	v_mov_b32_e32 v26, v42
	v_mov_b32_e32 v27, v38
	v_pk_mul_f32 v[44:45], v[44:45], v[44:45]
	v_mov_b32_e32 v46, v35
	v_pk_fma_f32 v[26:27], v[26:27], v[26:27], v[44:45]
	v_mov_b32_e32 v44, v40
	v_mov_b32_e32 v45, v36
	v_pk_fma_f32 v[26:27], v[44:45], v[44:45], v[26:27]
	v_mov_b32_e32 v44, v41
	v_mov_b32_e32 v45, v37
	v_mov_b32_e32 v47, v31
	v_pk_fma_f32 v[26:27], v[44:45], v[44:45], v[26:27]
	v_mov_b32_e32 v44, v34
	v_mov_b32_e32 v45, v30
	v_pk_mul_f32 v[46:47], v[46:47], v[46:47]
	v_add_f32_e32 v0, v26, v27
	v_pk_fma_f32 v[44:45], v[44:45], v[44:45], v[46:47]
	v_mov_b32_e32 v46, v32
	v_mov_b32_e32 v47, v28
	v_pk_fma_f32 v[44:45], v[46:47], v[46:47], v[44:45]
	v_mov_b32_e32 v46, v33
	v_mov_b32_e32 v47, v29
	v_pk_fma_f32 v[44:45], v[46:47], v[46:47], v[44:45]
	s_nop 0
	v_add_f32_e32 v0, v0, v44
	v_add_f32_e32 v0, v0, v45
	v_mov_b32_e32 v26, v0
	s_nop 1
	v_permlane32_swap_b32_e32 v0, v26
	s_waitcnt lgkmcnt(0)
	v_add_f32_e32 v0, v0, v26
	v_mov_b32_e32 v26, v0
	s_nop 1
	v_permlane16_swap_b32_e32 v0, v26
	s_waitcnt lgkmcnt(0)
	v_add_f32_e32 v0, v0, v26
	s_nop 1
	v_mov_b32_dpp v26, v0 row_ror:8 row_mask:0xf bank_mask:0xf
	s_waitcnt lgkmcnt(0)
	v_add_f32_e32 v0, v0, v26
	s_nop 1
	v_mov_b32_dpp v26, v0 row_ror:4 row_mask:0xf bank_mask:0xf
	s_waitcnt lgkmcnt(0)
	v_add_f32_e32 v0, v0, v26
	s_nop 1
	v_mov_b32_dpp v26, v0 row_ror:2 row_mask:0xf bank_mask:0xf
	s_waitcnt lgkmcnt(0)
	v_add_f32_e32 v0, v0, v26
	s_nop 1
	v_mov_b32_dpp v26, v0 row_ror:1 row_mask:0xf bank_mask:0xf
	s_waitcnt lgkmcnt(0)
	v_add_f32_e32 v0, v0, v26
	v_fmamk_f32 v0, v0, 0x3a800000, v170
	v_cmp_gt_f32_e32 vcc, s16, v0
	v_mul_f32_e32 v26, 0x4b800000, v0
	s_nop 0
	v_cndmask_b32_e32 v0, v0, v26, vcc
	v_rsq_f32_e32 v0, v0
	s_nop 0
	v_mul_f32_e32 v26, 0x45800000, v0
	v_cndmask_b32_e32 v0, v0, v26, vcc
	v_pk_mul_f32 v[42:43], v[42:43], v[0:1] op_sel_hi:[1,0]
	v_pk_mul_f32 v[40:41], v[40:41], v[0:1] op_sel_hi:[1,0]
	v_lshl_add_u64 v[26:27], v[24:25], 0, s[14:15]
	v_pk_mul_f32 v[38:39], v[38:39], v[0:1] op_sel_hi:[1,0]
	v_pk_mul_f32 v[36:37], v[36:37], v[0:1] op_sel_hi:[1,0]
	v_pk_mul_f32 v[34:35], v[34:35], v[0:1] op_sel_hi:[1,0]
	v_pk_mul_f32 v[32:33], v[32:33], v[0:1] op_sel_hi:[1,0]
	v_pk_mul_f32 v[30:31], v[30:31], v[0:1] op_sel_hi:[1,0]
	v_pk_mul_f32 v[28:29], v[28:29], v[0:1] op_sel_hi:[1,0]
	v_pk_mul_f32 v[42:43], v[100:101], v[42:43]
	v_pk_mul_f32 v[40:41], v[102:103], v[40:41]
	v_cvt_pk_bf16_f32 v42, v42, v43
	v_cvt_pk_bf16_f32 v43, v40, v41
	global_store_dwordx2 v[26:27], v[42:43], off
	v_pk_mul_f32 v[38:39], v[104:105], v[38:39]
	v_pk_mul_f32 v[36:37], v[106:107], v[36:37]
	v_cvt_pk_bf16_f32 v38, v38, v39
	v_cvt_pk_bf16_f32 v39, v36, v37
	global_store_dwordx2 v[26:27], v[38:39], off offset:512
	v_pk_mul_f32 v[34:35], v[34:35], v[108:109]
	v_pk_mul_f32 v[32:33], v[32:33], v[110:111]
	v_cvt_pk_bf16_f32 v34, v34, v35
	v_cvt_pk_bf16_f32 v35, v32, v33
	global_store_dwordx2 v[26:27], v[34:35], off offset:1024
	v_pk_mul_f32 v[30:31], v[30:31], v[112:113]
	v_pk_mul_f32 v[28:29], v[28:29], v[114:115]
	v_cvt_pk_bf16_f32 v30, v30, v31
	v_cvt_pk_bf16_f32 v31, v28, v29
	global_store_dwordx2 v[26:27], v[30:31], off offset:1536
	s_branch .LBB0_3260

; DI float bflo(unsigned u) { return __uint_as_float(u << 16); }
; DI float bfhi(unsigned u) { return __uint_as_float(u & 0xffff0000u); }
; DI void rowpass(const int wave_s, const float* __restrict__ xin, u16* __restrict__ X, const u16* __restrict__ Y, const float* __restrict__ gpost,
;                 const float* __restrict__ gpre, u16* __restrict__ HN, float* __restrict__ outf) {
;     ...
;   for (int row = blockIdx.x * 8 + wv; row < TOK; row += gridDim.x * 8) {
;     float4 x[4];
;     if (Y) {
;       float4 y[4];
;       float ss = 0.f;
; #pragma unroll
;       for (int j = 0; j < 4; ++j) {
;         const uint2 yu = *(const uint2*)(Y + (size_t)row * 1024 + j * 256 + lane * 4);
;         y[j] = make_float4(bflo(yu.x), bfhi(yu.x), bflo(yu.y), bfhi(yu.y));
;         ss += y[j].x * y[j].x + y[j].y * y[j].y + y[j].z * y[j].z + y[j].w * y[j].w;
;       }
;       ss = wsum(ss);
;       const float rs = rsqrtf(ss * (1.f / 1024.f) + 1e-6f);
; #pragma unroll
;       for (int j = 0; j < 4; ++j) {
;         const float4 g = *(const float4*)(gpost + j * 256 + lane * 4);
;         const uint2 xu = *(const uint2*)(X + (size_t)row * 1024 + j * 256 + lane * 4);
.LBB0_3525:
	v_readlane_b32 s4, v254, 10
	v_readlane_b32 s5, v254, 11
	s_waitcnt lgkmcnt(0)
	s_barrier
	v_mov_b32_e32 v0, v171
	s_nop 1
	global_load_dwordx2 v[2:3], v1, s[4:5] offset:24
	s_mov_b32 s4, s6
	v_readlane_b32 s5, v254, 26
	s_add_i32 s6, s4, s5
	s_cmpk_gt_i32 s6, 0x7fff
	s_waitcnt vmcnt(0)
	v_readfirstlane_b32 s4, v3
	v_readfirstlane_b32 s5, v2
	s_cbranch_scc1 .LBB0_3530
	s_lshl_b64 s[8:9], s[12:13], 2
	s_add_u32 s8, s5, s8
	v_lshlrev_b32_e32 v18, 2, v0
	s_addc_u32 s9, s4, s9
	v_ashrrev_i32_e32 v19, 31, v18
	v_lshl_add_u64 v[22:23], v[18:19], 2, s[8:9]
	s_mov_b64 s[4:5], 0x3000
	v_lshl_add_u64 v[14:15], v[22:23], 0, s[4:5]
	s_movk_i32 s4, 0x3000
	v_add_co_u32_e32 v10, vcc, s4, v22
	v_lshlrev_b64 v[24:25], 1, v[18:19]
	s_nop 0
	v_addc_co_u32_e32 v11, vcc, 0, v23, vcc
	flat_load_dwordx4 v[2:5], v[14:15] offset:1024
	flat_load_dwordx4 v[6:9], v[14:15] offset:2048
	s_nop 0
	flat_load_dwordx4 v[10:13], v[10:11]
	s_nop 0
	flat_load_dwordx4 v[14:17], v[14:15] offset:3072
	s_cmp_lg_u64 s[0:1], 0
	s_mov_b64 s[4:5], 0x4000
	v_lshl_add_u64 v[18:19], s[14:15], 0, v[24:25]
	v_lshl_add_u64 v[20:21], s[10:11], 0, v[24:25]
	s_cselect_b64 s[8:9], -1, 0
	v_lshl_add_u64 v[22:23], v[22:23], 0, s[4:5]
	v_lshl_add_u64 v[24:25], s[0:1], 0, v[24:25]
	flat_load_dwordx4 v[100:103], v[22:23]
	flat_load_dwordx4 v[104:107], v[22:23] offset:1024
	flat_load_dwordx4 v[108:111], v[22:23] offset:2048
	flat_load_dwordx4 v[112:115], v[22:23] offset:3072
	s_ashr_i32 s7, s6, 31
	s_lshl_b64 s[14:15], s[6:7], 11
	v_lshl_add_u64 v[132:133], v[18:19], 0, s[14:15]
	global_load_dwordx2 v[116:117], v[132:133], off
	global_load_dwordx2 v[118:119], v[132:133], off offset:512
	global_load_dwordx2 v[120:121], v[132:133], off offset:1024
	global_load_dwordx2 v[122:123], v[132:133], off offset:1536
	v_lshl_add_u64 v[132:133], v[20:21], 0, s[14:15]
	global_load_dwordx2 v[124:125], v[132:133], off
	global_load_dwordx2 v[126:127], v[132:133], off offset:512
	global_load_dwordx2 v[128:129], v[132:133], off offset:1024
	global_load_dwordx2 v[130:131], v[132:133], off offset:1536
	s_branch .LBB0_3528

; DI float bflo(unsigned u) { return __uint_as_float(u << 16); }
; DI float bfhi(unsigned u) { return __uint_as_float(u & 0xffff0000u); }
; DI void rowpass(const int wave_s, const float* __restrict__ xin, u16* __restrict__ X, const u16* __restrict__ Y, const float* __restrict__ gpost,
;                 const float* __restrict__ gpre, u16* __restrict__ HN, float* __restrict__ outf) {
;     ...
; #pragma unroll
;       for (int j = 0; j < 4; ++j) {
;         const uint2 yu = *(const uint2*)(Y + (size_t)row * 1024 + j * 256 + lane * 4);
;         y[j] = make_float4(bflo(yu.x), bfhi(yu.x), bflo(yu.y), bfhi(yu.y));
;         ss += y[j].x * y[j].x + y[j].y * y[j].y + y[j].z * y[j].z + y[j].w * y[j].w;
;       }
;       ss = wsum(ss);
;       const float rs = rsqrtf(ss * (1.f / 1024.f) + 1e-6f);
; #pragma unroll
;       for (int j = 0; j < 4; ++j) {
;         const float4 g = *(const float4*)(gpost + j * 256 + lane * 4);
;         const uint2 xu = *(const uint2*)(X + (size_t)row * 1024 + j * 256 + lane * 4);
;         x[j] = make_float4(bflo(xu.x), bfhi(xu.x), bflo(xu.y), bfhi(xu.y));
;         x[j].x += y[j].x * rs * g.x; x[j].y += y[j].y * rs * g.y; x[j].z += y[j].z * rs * g.z; x[j].w += y[j].w * rs * g.w;
;       }
;     } else {
; #pragma unroll
;       for (int j = 0; j < 4; ++j) x[j] = *(const float4*)(xin + (size_t)row * 1024 + j * 256 + lane * 4);
;     }
;     float ss2 = 0.f;
; #pragma unroll
;     for (int j = 0; j < 4; ++j) {
;       if (outf) *(float4*)(outf + (size_t)row * 1024 + j * 256 + lane * 4) = x[j];
;       else { uint2 xp; xp.x = pack2(x[j].x, x[j].y); xp.y = pack2(x[j].z, x[j].w); *(uint2*)(X + (size_t)row * 1024 + j * 256 + lane * 4) = xp; }
;       ss2 += x[j].x * x[j].x + x[j].y * x[j].y + x[j].z * x[j].z + x[j].w * x[j].w;
;     }
.Lrp1_nopf:
	s_mov_b32 s7, 0x800000
	s_andn2_b64 vcc, exec, s[8:9]
	v_and_b32_e32 v43, 0xffff0000, v28
	v_and_b32_e32 v47, 0xffff0000, v30
	v_lshlrev_b32_e32 v42, 16, v28
	v_lshlrev_b32_e32 v46, 16, v30
	v_and_b32_e32 v49, 0xffff0000, v32
	v_and_b32_e32 v51, 0xffff0000, v26
	v_mov_b32_e32 v58, v43
	v_mov_b32_e32 v59, v47
	v_lshlrev_b32_e32 v28, 16, v29
	v_lshlrev_b32_e32 v30, 16, v31
	v_lshlrev_b32_e32 v48, 16, v32
	v_lshlrev_b32_e32 v50, 16, v26
	v_mov_b32_e32 v56, v42
	v_mov_b32_e32 v57, v46
	v_mov_b32_e32 v66, v49
	v_mov_b32_e32 v67, v51
	v_pk_mul_f32 v[58:59], v[58:59], v[58:59]
	v_and_b32_e32 v29, 0xffff0000, v29
	v_and_b32_e32 v31, 0xffff0000, v31
	v_lshlrev_b32_e32 v32, 16, v33
	v_lshlrev_b32_e32 v26, 16, v27
	v_mov_b32_e32 v52, v28
	v_mov_b32_e32 v53, v30
	v_mov_b32_e32 v64, v48
	v_mov_b32_e32 v65, v50
	v_pk_mul_f32 v[66:67], v[66:67], v[66:67]
	v_pk_fma_f32 v[56:57], v[56:57], v[56:57], v[58:59]
	v_and_b32_e32 v33, 0xffff0000, v33
	v_and_b32_e32 v27, 0xffff0000, v27
	v_mov_b32_e32 v54, v29
	v_mov_b32_e32 v55, v31
	v_mov_b32_e32 v60, v32
	v_mov_b32_e32 v61, v26
	v_pk_fma_f32 v[58:59], v[64:65], v[64:65], v[66:67]
	v_pk_fma_f32 v[52:53], v[52:53], v[52:53], v[56:57]
	v_mov_b32_e32 v62, v33
	v_mov_b32_e32 v63, v27
	v_pk_fma_f32 v[56:57], v[60:61], v[60:61], v[58:59]
	v_pk_fma_f32 v[52:53], v[54:55], v[54:55], v[52:53]
	v_pk_fma_f32 v[54:55], v[62:63], v[62:63], v[56:57]
	v_add_f32_e32 v0, v52, v53
	v_add_f32_e32 v0, v0, v54
	v_add_f32_e32 v0, v0, v55
	v_mov_b32_e32 v52, v0
	s_nop 1
	v_permlane32_swap_b32_e32 v0, v52
	v_lshlrev_b32_e32 v56, 16, v38
	v_lshlrev_b32_e32 v58, 16, v39
	v_and_b32_e32 v59, 0xffff0000, v39
	v_lshlrev_b32_e32 v54, 16, v36
	s_waitcnt lgkmcnt(0)
	v_add_f32_e32 v0, v0, v52
	v_mov_b32_e32 v52, v0
	s_nop 1
	v_permlane16_swap_b32_e32 v0, v52
	v_lshlrev_b32_e32 v60, 16, v40
	v_lshlrev_b32_e32 v62, 16, v41
	v_and_b32_e32 v63, 0xffff0000, v41
	s_waitcnt lgkmcnt(0)
	v_add_f32_e32 v0, v0, v52
	s_nop 1
	v_mov_b32_dpp v53, v0 row_ror:8 row_mask:0xf bank_mask:0xf
	v_lshlrev_b32_e32 v52, 16, v34
	s_waitcnt lgkmcnt(0)
	v_add_f32_e32 v0, v0, v53
	s_nop 1
	v_mov_b32_dpp v55, v0 row_ror:4 row_mask:0xf bank_mask:0xf
	v_and_b32_e32 v53, 0xffff0000, v34
	v_lshlrev_b32_e32 v34, 16, v35
	v_and_b32_e32 v35, 0xffff0000, v35
	s_waitcnt lgkmcnt(0)
	v_add_f32_e32 v0, v0, v55
	s_nop 1
	v_mov_b32_dpp v57, v0 row_ror:2 row_mask:0xf bank_mask:0xf
	v_and_b32_e32 v55, 0xffff0000, v36
	v_lshlrev_b32_e32 v36, 16, v37
	v_and_b32_e32 v37, 0xffff0000, v37
	s_waitcnt lgkmcnt(0)
	v_add_f32_e32 v0, v0, v57
	s_nop 1
	v_mov_b32_dpp v61, v0 row_ror:1 row_mask:0xf bank_mask:0xf
	v_and_b32_e32 v57, 0xffff0000, v38
	s_waitcnt lgkmcnt(0)
	v_add_f32_e32 v0, v0, v61
	v_fmamk_f32 v0, v0, 0x3a800000, v170
	v_mul_f32_e32 v38, 0x4b800000, v0
	v_cmp_gt_f32_e64 s[4:5], s7, v0
	v_and_b32_e32 v61, 0xffff0000, v40
	s_nop 0
	v_cndmask_b32_e64 v0, v0, v38, s[4:5]
	v_rsq_f32_e32 v0, v0
	s_nop 0
	v_mul_f32_e32 v38, 0x45800000, v0
	v_cndmask_b32_e64 v0, v0, v38, s[4:5]
	v_pk_mul_f32 v[38:39], v[0:1], v[42:43] op_sel_hi:[0,1]
	v_pk_mul_f32 v[28:29], v[0:1], v[28:29] op_sel_hi:[0,1]
	v_pk_mul_f32 v[46:47], v[0:1], v[46:47] op_sel_hi:[0,1]
	v_pk_mul_f32 v[30:31], v[0:1], v[30:31] op_sel_hi:[0,1]
	v_pk_mul_f32 v[48:49], v[0:1], v[48:49] op_sel_hi:[0,1]
	v_pk_mul_f32 v[32:33], v[0:1], v[32:33] op_sel_hi:[0,1]
	v_pk_mul_f32 v[50:51], v[0:1], v[50:51] op_sel_hi:[0,1]
	v_pk_mul_f32 v[26:27], v[0:1], v[26:27] op_sel_hi:[0,1]
	v_pk_fma_f32 v[42:43], v[10:11], v[38:39], v[52:53]
	v_pk_fma_f32 v[40:41], v[12:13], v[28:29], v[34:35]
	v_pk_fma_f32 v[38:39], v[2:3], v[46:47], v[54:55]
	v_pk_fma_f32 v[36:37], v[4:5], v[30:31], v[36:37]
	v_pk_fma_f32 v[34:35], v[6:7], v[48:49], v[56:57]
	v_pk_fma_f32 v[32:33], v[32:33], v[8:9], v[58:59]
	v_pk_fma_f32 v[30:31], v[50:51], v[14:15], v[60:61]
	v_pk_fma_f32 v[28:29], v[26:27], v[16:17], v[62:63]
	v_cvt_pk_bf16_f32 v26, v42, v43
	v_cvt_pk_bf16_f32 v27, v40, v41
	v_cvt_pk_bf16_f32 v46, v38, v39
	v_cvt_pk_bf16_f32 v47, v36, v37
	v_cvt_pk_bf16_f32 v48, v34, v35
	v_cvt_pk_bf16_f32 v49, v32, v33
	v_cvt_pk_bf16_f32 v50, v30, v31
	v_cvt_pk_bf16_f32 v51, v28, v29
	global_store_dwordx2 v[44:45], v[26:27], off
	global_store_dwordx2 v[44:45], v[46:47], off offset:512
	global_store_dwordx2 v[44:45], v[48:49], off offset:1024
	global_store_dwordx2 v[44:45], v[50:51], off offset:1536
	s_cbranch_vccnz .LBB0_3527
; DI void rowpass(const int wave_s, const float* __restrict__ xin, u16* __restrict__ X, const u16* __restrict__ Y, const float* __restrict__ gpost,
;                 const float* __restrict__ gpre, u16* __restrict__ HN, float* __restrict__ outf) {
;     ...
;     if (HN) {
;       ss2 = wsum(ss2);
;       const float rs2 = rsqrtf(ss2 * (1.f / 1024.f) + 1e-6f);
; #pragma unroll
;       for (int j = 0; j < 4; ++j) {
;         const float4 g = *(const float4*)(gpre + j * 256 + lane * 4);
;         uint2 pk;
;         pk.x = pack2(x[j].x * rs2 * g.x, x[j].y * rs2 * g.y);
;         pk.y = pack2(x[j].z * rs2 * g.z, x[j].w * rs2 * g.w);
;         *(uint2*)(HN + (size_t)row * 1024 + j * 256 + lane * 4) = pk;
;       }
	v_mov_b32_e32 v44, v43
	v_mov_b32_e32 v45, v39
	v_mov_b32_e32 v26, v42
	v_mov_b32_e32 v27, v38
	v_pk_mul_f32 v[44:45], v[44:45], v[44:45]
	v_mov_b32_e32 v46, v35
	v_pk_fma_f32 v[26:27], v[26:27], v[26:27], v[44:45]
	v_mov_b32_e32 v44, v40
	v_mov_b32_e32 v45, v36
	v_pk_fma_f32 v[26:27], v[44:45], v[44:45], v[26:27]
	v_mov_b32_e32 v44, v41
	v_mov_b32_e32 v45, v37
	v_mov_b32_e32 v47, v31
	v_pk_fma_f32 v[26:27], v[44:45], v[44:45], v[26:27]
	v_mov_b32_e32 v44, v34
	v_mov_b32_e32 v45, v30
	v_pk_mul_f32 v[46:47], v[46:47], v[46:47]
	v_add_f32_e32 v0, v26, v27
	v_pk_fma_f32 v[44:45], v[44:45], v[44:45], v[46:47]
	v_mov_b32_e32 v46, v32
	v_mov_b32_e32 v47, v28
	v_pk_fma_f32 v[44:45], v[46:47], v[46:47], v[44:45]
	v_mov_b32_e32 v46, v33
	v_mov_b32_e32 v47, v29
	v_pk_fma_f32 v[44:45], v[46:47], v[46:47], v[44:45]
	s_nop 0
	v_add_f32_e32 v0, v0, v44
	v_add_f32_e32 v0, v0, v45
	v_mov_b32_e32 v26, v0
	s_nop 1
	v_permlane32_swap_b32_e32 v0, v26
	s_waitcnt lgkmcnt(0)
	v_add_f32_e32 v0, v0, v26
	v_mov_b32_e32 v26, v0
	s_nop 1
	v_permlane16_swap_b32_e32 v0, v26
	s_waitcnt lgkmcnt(0)
	v_add_f32_e32 v0, v0, v26
	s_nop 1
	v_mov_b32_dpp v26, v0 row_ror:8 row_mask:0xf bank_mask:0xf
	s_waitcnt lgkmcnt(0)
	v_add_f32_e32 v0, v0, v26
	s_nop 1
	v_mov_b32_dpp v26, v0 row_ror:4 row_mask:0xf bank_mask:0xf
	s_waitcnt lgkmcnt(0)
	v_add_f32_e32 v0, v0, v26
	s_nop 1
	v_mov_b32_dpp v26, v0 row_ror:2 row_mask:0xf bank_mask:0xf
	s_waitcnt lgkmcnt(0)
	v_add_f32_e32 v0, v0, v26
	s_nop 1
	v_mov_b32_dpp v26, v0 row_ror:1 row_mask:0xf bank_mask:0xf
	s_waitcnt lgkmcnt(0)
	v_add_f32_e32 v0, v0, v26
	v_fmamk_f32 v0, v0, 0x3a800000, v170
	v_cmp_gt_f32_e32 vcc, s7, v0
	v_mul_f32_e32 v26, 0x4b800000, v0
	s_nop 0
	v_cndmask_b32_e32 v0, v0, v26, vcc
	v_rsq_f32_e32 v0, v0
	s_nop 0
	v_mul_f32_e32 v26, 0x45800000, v0
	v_cndmask_b32_e32 v0, v0, v26, vcc
	v_pk_mul_f32 v[42:43], v[42:43], v[0:1] op_sel_hi:[1,0]
	v_pk_mul_f32 v[40:41], v[40:41], v[0:1] op_sel_hi:[1,0]
	v_lshl_add_u64 v[26:27], v[24:25], 0, s[14:15]
	v_pk_mul_f32 v[38:39], v[38:39], v[0:1] op_sel_hi:[1,0]
	v_pk_mul_f32 v[36:37], v[36:37], v[0:1] op_sel_hi:[1,0]
	v_pk_mul_f32 v[34:35], v[34:35], v[0:1] op_sel_hi:[1,0]
	v_pk_mul_f32 v[32:33], v[32:33], v[0:1] op_sel_hi:[1,0]
	v_pk_mul_f32 v[30:31], v[30:31], v[0:1] op_sel_hi:[1,0]
	v_pk_mul_f32 v[28:29], v[28:29], v[0:1] op_sel_hi:[1,0]
	v_pk_mul_f32 v[42:43], v[100:101], v[42:43]
	v_pk_mul_f32 v[40:41], v[102:103], v[40:41]
	v_cvt_pk_bf16_f32 v42, v42, v43
	v_cvt_pk_bf16_f32 v43, v40, v41
	global_store_dwordx2 v[26:27], v[42:43], off
	v_pk_mul_f32 v[38:39], v[104:105], v[38:39]
	v_pk_mul_f32 v[36:37], v[106:107], v[36:37]
	v_cvt_pk_bf16_f32 v38, v38, v39
	v_cvt_pk_bf16_f32 v39, v36, v37
	global_store_dwordx2 v[26:27], v[38:39], off offset:512
	v_pk_mul_f32 v[34:35], v[34:35], v[108:109]
	v_pk_mul_f32 v[32:33], v[32:33], v[110:111]
	v_cvt_pk_bf16_f32 v34, v34, v35
	v_cvt_pk_bf16_f32 v35, v32, v33
	global_store_dwordx2 v[26:27], v[34:35], off offset:1024
	v_pk_mul_f32 v[30:31], v[30:31], v[112:113]
	v_pk_mul_f32 v[28:29], v[28:29], v[114:115]
	v_cvt_pk_bf16_f32 v30, v30, v31
	v_cvt_pk_bf16_f32 v31, v28, v29
	global_store_dwordx2 v[26:27], v[30:31], off offset:1536
	s_branch .LBB0_3527

; DI float bflo(unsigned u) { return __uint_as_float(u << 16); }
; DI float bfhi(unsigned u) { return __uint_as_float(u & 0xffff0000u); }
; DI void rowpass(const int wave_s, const float* __restrict__ xin, u16* __restrict__ X, const u16* __restrict__ Y, const float* __restrict__ gpost,
;                 const float* __restrict__ gpre, u16* __restrict__ HN, float* __restrict__ outf) {
;     ...
;     if (Y) {
;       float4 y[4];
;       float ss = 0.f;
; #pragma unroll
;       for (int j = 0; j < 4; ++j) {
;         const uint2 yu = *(const uint2*)(Y + (size_t)row * 1024 + j * 256 + lane * 4);
;         y[j] = make_float4(bflo(yu.x), bfhi(yu.x), bflo(yu.y), bfhi(yu.y));
;         ss += y[j].x * y[j].x + y[j].y * y[j].y + y[j].z * y[j].z + y[j].w * y[j].w;
;       }
;       ss = wsum(ss);
;       const float rs = rsqrtf(ss * (1.f / 1024.f) + 1e-6f);
; #pragma unroll
;       for (int j = 0; j < 4; ++j) {
;         const float4 g = *(const float4*)(gpost + j * 256 + lane * 4);
;         const uint2 xu = *(const uint2*)(X + (size_t)row * 1024 + j * 256 + lane * 4);
;         x[j] = make_float4(bflo(xu.x), bfhi(xu.x), bflo(xu.y), bfhi(xu.y));
;         x[j].x += y[j].x * rs * g.x; x[j].y += y[j].y * rs * g.y; x[j].z += y[j].z * rs * g.z; x[j].w += y[j].w * rs * g.w;
;       }
;     } else {
; #pragma unroll
;       for (int j = 0; j < 4; ++j) x[j] = *(const float4*)(xin + (size_t)row * 1024 + j * 256 + lane * 4);
;     }
;     float ss2 = 0.f;
; #pragma unroll
;     for (int j = 0; j < 4; ++j) {
;       if (outf) *(float4*)(outf + (size_t)row * 1024 + j * 256 + lane * 4) = x[j];
;       else { uint2 xp; xp.x = pack2(x[j].x, x[j].y); xp.y = pack2(x[j].z, x[j].w); *(uint2*)(X + (size_t)row * 1024 + j * 256 + lane * 4) = xp; }
;       ss2 += x[j].x * x[j].x + x[j].y * x[j].y + x[j].z * x[j].z + x[j].w * x[j].w;
;     }
.LBB0_3761:
	s_ashr_i32 s15, s14, 31
	s_lshl_b64 s[10:11], s[14:15], 11
	v_lshl_add_u64 v[18:19], v[34:35], 0, s[10:11]
	global_load_dwordx2 v[20:21], v[18:19], off
	v_lshl_add_u64 v[44:45], v[36:37], 0, s[10:11]
	global_load_dwordx2 v[50:51], v[44:45], off
	s_lshl_b64 s[4:5], s[14:15], 12
	global_load_dwordx2 v[52:53], v[44:45], off offset:512
	s_waitcnt vmcnt(0) lgkmcnt(0)
	v_lshlrev_b32_e32 v22, 16, v20
	v_and_b32_e32 v23, 0xffff0000, v20
	v_lshlrev_b32_e32 v24, 16, v21
	v_and_b32_e32 v25, 0xffff0000, v21
	global_load_dwordx2 v[20:21], v[18:19], off offset:512
	v_mov_b32_e32 v62, v23
	v_mov_b32_e32 v58, v22
	v_lshlrev_b32_e32 v56, 16, v50
	v_and_b32_e32 v57, 0xffff0000, v50
	v_lshlrev_b32_e32 v60, 16, v51
	v_and_b32_e32 v61, 0xffff0000, v51
	v_mov_b32_e32 v50, v24
	v_mov_b32_e32 v54, v25
	s_waitcnt vmcnt(0) lgkmcnt(0)
	v_lshlrev_b32_e32 v26, 16, v20
	v_and_b32_e32 v27, 0xffff0000, v20
	v_lshlrev_b32_e32 v28, 16, v21
	v_and_b32_e32 v29, 0xffff0000, v21
	global_load_dwordx2 v[20:21], v[18:19], off offset:1024
	v_mov_b32_e32 v63, v27
	v_mov_b32_e32 v59, v26
	v_pk_mul_f32 v[62:63], v[62:63], v[62:63]
	v_mov_b32_e32 v51, v28
	v_pk_fma_f32 v[58:59], v[58:59], v[58:59], v[62:63]
	v_mov_b32_e32 v55, v29
	v_pk_fma_f32 v[50:51], v[50:51], v[50:51], v[58:59]
	s_waitcnt vmcnt(0) lgkmcnt(0)
	v_lshlrev_b32_e32 v30, 16, v20
	v_and_b32_e32 v46, 0xffff0000, v20
	v_lshlrev_b32_e32 v32, 16, v21
	v_and_b32_e32 v48, 0xffff0000, v21
	global_load_dwordx2 v[20:21], v[18:19], off offset:1536
	v_pk_fma_f32 v[58:59], v[54:55], v[54:55], v[50:51]
	global_load_dwordx2 v[54:55], v[44:45], off offset:1024
	global_load_dwordx2 v[50:51], v[44:45], off offset:1536
	v_add_f32_e32 v0, v58, v59
	s_waitcnt vmcnt(0) lgkmcnt(0)
	v_and_b32_e32 v19, 0xffff0000, v20
	v_lshlrev_b32_e32 v18, 16, v20
	v_mov_b32_e32 v47, v19
	v_lshlrev_b32_e32 v20, 16, v21
	v_mov_b32_e32 v31, v18
	v_pk_mul_f32 v[62:63], v[46:47], v[46:47]
	v_and_b32_e32 v21, 0xffff0000, v21
	v_mov_b32_e32 v33, v20
	v_pk_fma_f32 v[62:63], v[30:31], v[30:31], v[62:63]
	v_mov_b32_e32 v49, v21
	v_pk_fma_f32 v[62:63], v[32:33], v[32:33], v[62:63]
	s_nop 0
	v_pk_fma_f32 v[62:63], v[48:49], v[48:49], v[62:63]
	s_nop 0
	v_add_f32_e32 v0, v0, v62
	v_add_f32_e32 v0, v0, v63
	v_mov_b32_e32 v31, v0
	s_nop 1
	v_permlane32_swap_b32_e32 v0, v31
	s_waitcnt lgkmcnt(0)
	v_add_f32_e32 v0, v0, v31
	v_mov_b32_e32 v31, v0
	s_nop 1
	v_permlane16_swap_b32_e32 v0, v31
	s_waitcnt lgkmcnt(0)
	v_add_f32_e32 v0, v0, v31
	s_nop 1
	v_mov_b32_dpp v31, v0 row_ror:8 row_mask:0xf bank_mask:0xf
	s_waitcnt lgkmcnt(0)
	v_add_f32_e32 v0, v0, v31
	s_nop 1
	v_mov_b32_dpp v31, v0 row_ror:4 row_mask:0xf bank_mask:0xf
	s_waitcnt lgkmcnt(0)
	v_add_f32_e32 v0, v0, v31
	s_nop 1
	v_mov_b32_dpp v31, v0 row_ror:2 row_mask:0xf bank_mask:0xf
	s_waitcnt lgkmcnt(0)
	v_add_f32_e32 v0, v0, v31
	s_nop 1
	v_mov_b32_dpp v31, v0 row_ror:1 row_mask:0xf bank_mask:0xf
	s_waitcnt lgkmcnt(0)
	v_add_f32_e32 v0, v0, v31
	v_fmamk_f32 v0, v0, 0x3a800000, v170
	v_cmp_gt_f32_e32 vcc, s33, v0
	v_mul_f32_e32 v31, 0x4b800000, v0
	s_nop 0
	v_cndmask_b32_e32 v0, v0, v31, vcc
	v_rsq_f32_e32 v0, v0
	s_nop 0
	v_mul_f32_e32 v31, 0x45800000, v0
	v_cndmask_b32_e32 v58, v0, v31, vcc
	v_pk_mul_f32 v[22:23], v[58:59], v[22:23] op_sel_hi:[0,1]
	v_pk_mul_f32 v[24:25], v[58:59], v[24:25] op_sel_hi:[0,1]
	v_cndmask_b32_e64 v0, 0, 1, s[0:1]
	v_pk_fma_f32 v[22:23], v[10:11], v[22:23], v[56:57]
	v_pk_fma_f32 v[24:25], v[12:13], v[24:25], v[60:61]
	v_lshl_add_u64 v[56:57], v[38:39], 0, s[4:5]
	v_cmp_ne_u32_e64 s[4:5], 1, v0
	s_andn2_b64 vcc, exec, s[0:1]
	s_cbranch_vccnz .LBB0_3775
	global_store_dwordx4 v[56:57], v[22:25], off
	s_cbranch_execnz .LBB0_3764
.LBB0_3763:
	v_cvt_pk_bf16_f32 v60, v22, v23
	v_cvt_pk_bf16_f32 v61, v24, v25
	global_store_dwordx2 v[44:45], v[60:61], off

; DI void rowpass(const int wave_s, const float* __restrict__ xin, u16* __restrict__ X, const u16* __restrict__ Y, const float* __restrict__ gpost,
;                 const float* __restrict__ gpre, u16* __restrict__ HN, float* __restrict__ outf) {
;     ...
;       else { uint2 xp; xp.x = pack2(x[j].x, x[j].y); xp.y = pack2(x[j].z, x[j].w); *(uint2*)(X + (size_t)row * 1024 + j * 256 + lane * 4) = xp; }
.LBB0_3766:
	v_cvt_pk_bf16_f32 v52, v26, v27
	v_cvt_pk_bf16_f32 v53, v28, v29
	global_store_dwordx2 v[44:45], v[52:53], off offset:512

; DI void rowpass(const int wave_s, const float* __restrict__ xin, u16* __restrict__ X, const u16* __restrict__ Y, const float* __restrict__ gpost,
;                 const float* __restrict__ gpre, u16* __restrict__ HN, float* __restrict__ outf) {
;     ...
;       else { uint2 xp; xp.x = pack2(x[j].x, x[j].y); xp.y = pack2(x[j].z, x[j].w); *(uint2*)(X + (size_t)row * 1024 + j * 256 + lane * 4) = xp; }
.LBB0_3769:
	v_cvt_pk_bf16_f32 v46, v30, v31
	v_cvt_pk_bf16_f32 v47, v32, v33
	global_store_dwordx2 v[44:45], v[46:47], off offset:1024

; DI void rowpass(const int wave_s, const float* __restrict__ xin, u16* __restrict__ X, const u16* __restrict__ Y, const float* __restrict__ gpost,
;                 const float* __restrict__ gpre, u16* __restrict__ HN, float* __restrict__ outf) {
;     ...
;       else { uint2 xp; xp.x = pack2(x[j].x, x[j].y); xp.y = pack2(x[j].z, x[j].w); *(uint2*)(X + (size_t)row * 1024 + j * 256 + lane * 4) = xp; }
;       ss2 += x[j].x * x[j].x + x[j].y * x[j].y + x[j].z * x[j].z + x[j].w * x[j].w;
;     }
;     if (HN) {
;       ss2 = wsum(ss2);
;       const float rs2 = rsqrtf(ss2 * (1.f / 1024.f) + 1e-6f);
; #pragma unroll
;       for (int j = 0; j < 4; ++j) {
;         const float4 g = *(const float4*)(gpre + j * 256 + lane * 4);
;         uint2 pk;
;         pk.x = pack2(x[j].x * rs2 * g.x, x[j].y * rs2 * g.y);
;         pk.y = pack2(x[j].z * rs2 * g.z, x[j].w * rs2 * g.w);
;         *(uint2*)(HN + (size_t)row * 1024 + j * 256 + lane * 4) = pk;
;       }
.LBB0_3772:
	v_cvt_pk_bf16_f32 v46, v18, v19
	v_cvt_pk_bf16_f32 v47, v20, v21
	global_store_dwordx2 v[44:45], v[46:47], off offset:1536
.LBB0_3773:
	s_andn2_b64 vcc, exec, s[8:9]
	s_cbranch_vccnz .LBB0_3760
	v_pk_mul_f32 v[44:45], v[22:23], v[22:23]
	v_pk_mul_f32 v[46:47], v[24:25], v[24:25]
	v_add_f32_e32 v44, v44, v45
	v_pk_mul_f32 v[48:49], v[26:27], v[26:27]
	v_add_f32_e32 v44, v46, v44
	v_add_f32_e32 v0, v48, v49
	v_add_f32_e32 v44, v47, v44
	global_load_dwordx4 v[46:49], v[40:41], off
	v_pk_mul_f32 v[50:51], v[28:29], v[28:29]
	v_pk_mul_f32 v[52:53], v[30:31], v[30:31]
	v_add_f32_e32 v0, v50, v0
	v_add_f32_e32 v0, v51, v0
	v_pk_mul_f32 v[54:55], v[32:33], v[32:33]
	v_add_f32_e32 v0, v44, v0
	v_add_f32_e32 v44, v52, v53
	v_add_f32_e32 v44, v44, v54
	v_pk_mul_f32 v[56:57], v[18:19], v[18:19]
	v_add_f32_e32 v44, v55, v44
	v_pk_mul_f32 v[58:59], v[20:21], v[20:21]
	v_add_f32_e32 v0, v0, v44
	v_add_f32_e32 v44, v56, v57
	v_add_f32_e32 v44, v44, v58
	v_add_f32_e32 v44, v59, v44
	v_add_f32_e32 v0, v0, v44
	v_mov_b32_e32 v44, v0
	s_nop 1
	v_permlane32_swap_b32_e32 v0, v44
	s_waitcnt lgkmcnt(0)
	v_add_f32_e32 v0, v0, v44
	v_mov_b32_e32 v44, v0
	s_nop 1
	v_permlane16_swap_b32_e32 v0, v44
	s_waitcnt lgkmcnt(0)
	v_add_f32_e32 v0, v0, v44
	s_nop 1
	v_mov_b32_dpp v44, v0 row_ror:8 row_mask:0xf bank_mask:0xf
	s_waitcnt lgkmcnt(0)
	v_add_f32_e32 v0, v0, v44
	s_nop 1
	v_mov_b32_dpp v44, v0 row_ror:4 row_mask:0xf bank_mask:0xf
	s_waitcnt lgkmcnt(0)
	v_add_f32_e32 v0, v0, v44
	s_nop 1
	v_mov_b32_dpp v44, v0 row_ror:2 row_mask:0xf bank_mask:0xf
	s_waitcnt lgkmcnt(0)
	v_add_f32_e32 v0, v0, v44
	s_nop 1
	v_mov_b32_dpp v44, v0 row_ror:1 row_mask:0xf bank_mask:0xf
	s_waitcnt lgkmcnt(0)
	v_add_f32_e32 v0, v0, v44
	v_fmamk_f32 v0, v0, 0x3a800000, v170
	v_cmp_gt_f32_e32 vcc, s33, v0
	v_mul_f32_e32 v44, 0x4b800000, v0
	s_nop 0
	v_cndmask_b32_e32 v0, v0, v44, vcc
	v_rsq_f32_e32 v0, v0
	s_nop 0
	v_mul_f32_e32 v44, 0x45800000, v0
	v_cndmask_b32_e32 v0, v0, v44, vcc
	v_pk_mul_f32 v[22:23], v[22:23], v[0:1] op_sel_hi:[1,0]
	v_pk_mul_f32 v[24:25], v[24:25], v[0:1] op_sel_hi:[1,0]
	v_lshl_add_u64 v[44:45], v[42:43], 0, s[10:11]
	v_pk_mul_f32 v[26:27], v[26:27], v[0:1] op_sel_hi:[1,0]
	v_pk_mul_f32 v[18:19], v[18:19], v[0:1] op_sel_hi:[1,0]
	v_pk_mul_f32 v[20:21], v[20:21], v[0:1] op_sel_hi:[1,0]
	s_waitcnt vmcnt(0)
	v_pk_mul_f32 v[22:23], v[46:47], v[22:23]
	v_pk_mul_f32 v[24:25], v[48:49], v[24:25]
	v_cvt_pk_bf16_f32 v22, v22, v23
	v_cvt_pk_bf16_f32 v23, v24, v25
	global_store_dwordx2 v[44:45], v[22:23], off
	global_load_dwordx4 v[22:25], v[40:41], off offset:1024
	s_waitcnt vmcnt(0) lgkmcnt(0)
	v_pk_mul_f32 v[22:23], v[22:23], v[26:27]
	v_pk_mul_f32 v[26:27], v[28:29], v[0:1] op_sel_hi:[1,0]
	v_cvt_pk_bf16_f32 v22, v22, v23
	v_pk_mul_f32 v[24:25], v[24:25], v[26:27]
	v_pk_mul_f32 v[26:27], v[30:31], v[0:1] op_sel_hi:[1,0]
	v_cvt_pk_bf16_f32 v23, v24, v25
	global_store_dwordx2 v[44:45], v[22:23], off offset:512
	global_load_dwordx4 v[22:25], v[40:41], off offset:2048
	s_waitcnt vmcnt(0) lgkmcnt(0)
	v_pk_mul_f32 v[22:23], v[26:27], v[22:23]
	v_pk_mul_f32 v[26:27], v[32:33], v[0:1] op_sel_hi:[1,0]
	v_cvt_pk_bf16_f32 v22, v22, v23
	v_pk_mul_f32 v[24:25], v[26:27], v[24:25]
	s_nop 0
	v_cvt_pk_bf16_f32 v23, v24, v25
	global_store_dwordx2 v[44:45], v[22:23], off offset:1024
	global_load_dwordx4 v[22:25], v[40:41], off offset:3072
	s_waitcnt vmcnt(0) lgkmcnt(0)
	v_pk_mul_f32 v[18:19], v[18:19], v[22:23]
	v_pk_mul_f32 v[20:21], v[20:21], v[24:25]
	v_cvt_pk_bf16_f32 v18, v18, v19
	v_cvt_pk_bf16_f32 v19, v20, v21
	global_store_dwordx2 v[44:45], v[18:19], off offset:1536
	s_branch .LBB0_3760
